# v28 + the same 4-deep LDS read pipelining in six more epilogue chains (QKV, MLA-down, MLA-up bf16 store chains)
# speedup vs baseline: 1.0038x; 1.0038x over previous
.LBB0_573:
	s_or_b64 exec, exec, s[20:21]
	v_mov_b32_e32 v0, v206
	s_waitcnt lgkmcnt(0)
	s_barrier
	v_mov_b32_e32 v2, v206
	v_lshlrev_b32_e32 v0, 2, v0
	v_and_b32_e32 v0, 0xfc, v0
	v_ashrrev_i32_e32 v5, 2, v2
	v_and_b32_e32 v8, -16, v5
	v_lshlrev_b32_e32 v4, 2, v0
	v_lshlrev_b32_e32 v0, 1, v0
	v_mad_u64_u32 v[6:7], s[20:21], v8, s36, v[4:5]
	v_lshl_add_u64 v[2:3], s[22:23], 0, v[0:1]
	v_add_u32_e32 v0, 0x80, v8
	ds_read_b128 v[236:239], v6
	ds_read_b128 v[240:243], v6 offset:1040
	ds_read_b128 v[244:247], v6 offset:2080
	ds_read_b128 v[248:251], v6 offset:3120
	s_waitcnt lgkmcnt(3)
	v_cvt_pk_bf16_f32 v236, v236, v237
	v_cvt_pk_bf16_f32 v237, v238, v239
	v_mad_i64_i32 v[12:13], s[20:21], v0, s4, v[2:3]
	global_store_dwordx2 v[12:13], v[236:237], off
	v_add_u32_e32 v0, 0x81, v8
	ds_read_b128 v[236:239], v6 offset:4160
	s_waitcnt lgkmcnt(3)
	v_cvt_pk_bf16_f32 v240, v240, v241
	v_cvt_pk_bf16_f32 v241, v242, v243
	v_mad_i64_i32 v[12:13], s[20:21], v0, s4, v[2:3]
	global_store_dwordx2 v[12:13], v[240:241], off
	v_add_u32_e32 v0, 0x82, v8
	ds_read_b128 v[240:243], v6 offset:5200
	s_waitcnt lgkmcnt(3)
	v_cvt_pk_bf16_f32 v244, v244, v245
	v_cvt_pk_bf16_f32 v245, v246, v247
	v_mad_i64_i32 v[12:13], s[20:21], v0, s4, v[2:3]
	global_store_dwordx2 v[12:13], v[244:245], off
	v_add_u32_e32 v0, 0x83, v8
	ds_read_b128 v[244:247], v6 offset:6240
	s_waitcnt lgkmcnt(3)
	v_cvt_pk_bf16_f32 v248, v248, v249
	v_cvt_pk_bf16_f32 v249, v250, v251
	v_mad_i64_i32 v[12:13], s[20:21], v0, s4, v[2:3]
	global_store_dwordx2 v[12:13], v[248:249], off
	v_add_u32_e32 v0, 0x84, v8
	ds_read_b128 v[248:251], v6 offset:7280
	s_waitcnt lgkmcnt(3)
	v_cvt_pk_bf16_f32 v236, v236, v237
	v_cvt_pk_bf16_f32 v237, v238, v239
	v_mad_i64_i32 v[12:13], s[20:21], v0, s4, v[2:3]
	global_store_dwordx2 v[12:13], v[236:237], off
	v_add_u32_e32 v0, 0x85, v8
	ds_read_b128 v[236:239], v6 offset:8320
	s_waitcnt lgkmcnt(3)
	v_cvt_pk_bf16_f32 v240, v240, v241
	v_cvt_pk_bf16_f32 v241, v242, v243
	v_mad_i64_i32 v[12:13], s[20:21], v0, s4, v[2:3]
	global_store_dwordx2 v[12:13], v[240:241], off
	v_add_u32_e32 v0, 0x86, v8
	ds_read_b128 v[240:243], v6 offset:9360
	s_waitcnt lgkmcnt(3)
	v_cvt_pk_bf16_f32 v244, v244, v245
	v_cvt_pk_bf16_f32 v245, v246, v247
	v_mad_i64_i32 v[12:13], s[20:21], v0, s4, v[2:3]
	global_store_dwordx2 v[12:13], v[244:245], off
	v_add_u32_e32 v0, 0x87, v8
	ds_read_b128 v[244:247], v6 offset:10400
	s_waitcnt lgkmcnt(3)
	v_cvt_pk_bf16_f32 v248, v248, v249
	v_cvt_pk_bf16_f32 v249, v250, v251
	v_mad_i64_i32 v[12:13], s[20:21], v0, s4, v[2:3]
	global_store_dwordx2 v[12:13], v[248:249], off
	v_add_u32_e32 v0, 0x88, v8
	ds_read_b128 v[248:251], v6 offset:11440
	s_waitcnt lgkmcnt(3)
	v_cvt_pk_bf16_f32 v236, v236, v237
	v_cvt_pk_bf16_f32 v237, v238, v239
	v_mad_i64_i32 v[12:13], s[20:21], v0, s4, v[2:3]
	global_store_dwordx2 v[12:13], v[236:237], off
	v_add_u32_e32 v0, 0x89, v8
	ds_read_b128 v[236:239], v6 offset:12480
	s_waitcnt lgkmcnt(3)
	v_cvt_pk_bf16_f32 v240, v240, v241
	v_cvt_pk_bf16_f32 v241, v242, v243
	v_mad_i64_i32 v[12:13], s[20:21], v0, s4, v[2:3]
	global_store_dwordx2 v[12:13], v[240:241], off
	v_add_u32_e32 v0, 0x8a, v8
	ds_read_b128 v[240:243], v6 offset:13520
	s_waitcnt lgkmcnt(3)
	v_cvt_pk_bf16_f32 v244, v244, v245
	v_cvt_pk_bf16_f32 v245, v246, v247
	v_mad_i64_i32 v[12:13], s[20:21], v0, s4, v[2:3]
	global_store_dwordx2 v[12:13], v[244:245], off
	v_add_u32_e32 v0, 0x8b, v8
	ds_read_b128 v[244:247], v6 offset:14560
	s_waitcnt lgkmcnt(3)
	v_cvt_pk_bf16_f32 v248, v248, v249
	v_cvt_pk_bf16_f32 v249, v250, v251
	v_mad_i64_i32 v[12:13], s[20:21], v0, s4, v[2:3]
	global_store_dwordx2 v[12:13], v[248:249], off
	v_add_u32_e32 v0, 0x8c, v8
	s_waitcnt lgkmcnt(2)
	v_cvt_pk_bf16_f32 v236, v236, v237
	v_cvt_pk_bf16_f32 v237, v238, v239
	v_mad_i64_i32 v[12:13], s[20:21], v0, s4, v[2:3]
	global_store_dwordx2 v[12:13], v[236:237], off
	v_add_u32_e32 v0, 0x8d, v8
	s_waitcnt lgkmcnt(1)
	v_cvt_pk_bf16_f32 v10, v240, v241
	v_cvt_pk_bf16_f32 v11, v242, v243
	v_mad_i64_i32 v[12:13], s[20:21], v0, s4, v[2:3]
	v_add_u32_e32 v0, 0x8e, v8
	s_waitcnt lgkmcnt(0)
	v_cvt_pk_bf16_f32 v244, v244, v245
	v_cvt_pk_bf16_f32 v245, v246, v247
	v_mad_i64_i32 v[8:9], s[20:21], v0, s4, v[2:3]
	v_or_b32_e32 v0, 15, v5
	global_store_dwordx2 v[8:9], v[244:245], off
	v_add_u32_e32 v8, 0x80, v0
	v_mad_u64_u32 v[4:5], s[20:21], v0, s36, v[4:5]
	v_mad_i64_i32 v[2:3], s[20:21], v8, s4, v[2:3]
	ds_read_b128 v[4:7], v4
	s_add_i32 s26, s26, 1
	v_readlane_b32 s20, v253, 56
	global_store_dwordx2 v[12:13], v[10:11], off
	s_waitcnt lgkmcnt(0)
	v_cvt_pk_bf16_f32 v4, v4, v5
	v_cvt_pk_bf16_f32 v5, v6, v7
	global_store_dwordx2 v[2:3], v[4:5], off
	s_barrier
	s_waitcnt vmcnt(0)
	s_mul_i32 s20, s26, s20
	v_readlane_b32 s21, v254, 45
	s_add_i32 s27, s20, s21
	s_cmp_gt_u32 s27, 26
	s_cbranch_scc1 .LBB0_703

.LBB0_592:
	s_or_b64 exec, exec, s[20:21]
	s_waitcnt lgkmcnt(0)
	s_barrier
	s_load_dwordx16 s[4:19], s[0:1], 0xa8
	v_mov_b32_e32 v0, v206
	s_mul_i32 s21, s28, 0x600
	s_mul_hi_i32 s20, s28, 0x600
	s_waitcnt lgkmcnt(0)
	s_add_u32 s27, s18, s21
	v_mov_b32_e32 v2, v206
	v_lshlrev_b32_e32 v0, 2, v0
	s_addc_u32 s28, s19, s20
	s_lshl_b64 s[20:21], s[22:23], 1
	v_and_b32_e32 v0, 0xfc, v0
	v_ashrrev_i32_e32 v9, 2, v2
	s_add_u32 s22, s27, s20
	v_and_b32_e32 v10, -16, v9
	v_lshlrev_b32_e32 v4, 2, v0
	s_addc_u32 s23, s28, s21
	v_lshlrev_b32_e32 v0, 1, v0
	v_mad_u64_u32 v[6:7], s[20:21], v10, s36, v[4:5]
	v_lshl_add_u64 v[2:3], s[22:23], 0, v[0:1]
	ds_read_b128 v[236:239], v6
	ds_read_b128 v[240:243], v6 offset:1040
	ds_read_b128 v[244:247], v6 offset:2080
	ds_read_b128 v[248:251], v6 offset:3120
	s_movk_i32 s4, 0x600
	s_waitcnt lgkmcnt(3)
	v_cvt_pk_bf16_f32 v236, v236, v237
	v_cvt_pk_bf16_f32 v237, v238, v239
	v_mad_i64_i32 v[14:15], s[20:21], v10, s4, v[2:3]
	global_store_dwordx2 v[14:15], v[236:237], off
	v_or_b32_e32 v0, 1, v10
	ds_read_b128 v[236:239], v6 offset:4160
	s_waitcnt lgkmcnt(3)
	v_cvt_pk_bf16_f32 v240, v240, v241
	v_cvt_pk_bf16_f32 v241, v242, v243
	v_mad_i64_i32 v[14:15], s[20:21], v0, s4, v[2:3]
	global_store_dwordx2 v[14:15], v[240:241], off
	v_or_b32_e32 v0, 2, v10
	ds_read_b128 v[240:243], v6 offset:5200
	s_waitcnt lgkmcnt(3)
	v_cvt_pk_bf16_f32 v244, v244, v245
	v_cvt_pk_bf16_f32 v245, v246, v247
	v_mad_i64_i32 v[14:15], s[20:21], v0, s4, v[2:3]
	global_store_dwordx2 v[14:15], v[244:245], off
	v_or_b32_e32 v0, 3, v10
	ds_read_b128 v[244:247], v6 offset:6240
	s_waitcnt lgkmcnt(3)
	v_cvt_pk_bf16_f32 v248, v248, v249
	v_cvt_pk_bf16_f32 v249, v250, v251
	v_mad_i64_i32 v[14:15], s[20:21], v0, s4, v[2:3]
	global_store_dwordx2 v[14:15], v[248:249], off
	v_or_b32_e32 v0, 4, v10
	ds_read_b128 v[248:251], v6 offset:7280
	s_waitcnt lgkmcnt(3)
	v_cvt_pk_bf16_f32 v236, v236, v237
	v_cvt_pk_bf16_f32 v237, v238, v239
	v_mad_i64_i32 v[14:15], s[20:21], v0, s4, v[2:3]
	global_store_dwordx2 v[14:15], v[236:237], off
	v_or_b32_e32 v0, 5, v10
	ds_read_b128 v[236:239], v6 offset:8320
	s_waitcnt lgkmcnt(3)
	v_cvt_pk_bf16_f32 v240, v240, v241
	v_cvt_pk_bf16_f32 v241, v242, v243
	v_mad_i64_i32 v[14:15], s[20:21], v0, s4, v[2:3]
	global_store_dwordx2 v[14:15], v[240:241], off
	v_or_b32_e32 v0, 6, v10
	ds_read_b128 v[240:243], v6 offset:9360
	s_waitcnt lgkmcnt(3)
	v_cvt_pk_bf16_f32 v244, v244, v245
	v_cvt_pk_bf16_f32 v245, v246, v247
	v_mad_i64_i32 v[14:15], s[20:21], v0, s4, v[2:3]
	global_store_dwordx2 v[14:15], v[244:245], off
	v_or_b32_e32 v0, 7, v10
	ds_read_b128 v[244:247], v6 offset:10400
	s_waitcnt lgkmcnt(3)
	v_cvt_pk_bf16_f32 v248, v248, v249
	v_cvt_pk_bf16_f32 v249, v250, v251
	v_mad_i64_i32 v[14:15], s[20:21], v0, s4, v[2:3]
	global_store_dwordx2 v[14:15], v[248:249], off
	v_or_b32_e32 v0, 8, v10
	ds_read_b128 v[248:251], v6 offset:11440
	s_waitcnt lgkmcnt(3)
	v_cvt_pk_bf16_f32 v236, v236, v237
	v_cvt_pk_bf16_f32 v237, v238, v239
	v_mad_i64_i32 v[14:15], s[20:21], v0, s4, v[2:3]
	global_store_dwordx2 v[14:15], v[236:237], off
	v_or_b32_e32 v0, 9, v10
	ds_read_b128 v[236:239], v6 offset:12480
	s_waitcnt lgkmcnt(3)
	v_cvt_pk_bf16_f32 v240, v240, v241
	v_cvt_pk_bf16_f32 v241, v242, v243
	v_mad_i64_i32 v[14:15], s[20:21], v0, s4, v[2:3]
	global_store_dwordx2 v[14:15], v[240:241], off
	v_or_b32_e32 v0, 10, v10
	ds_read_b128 v[240:243], v6 offset:13520
	s_waitcnt lgkmcnt(3)
	v_cvt_pk_bf16_f32 v244, v244, v245
	v_cvt_pk_bf16_f32 v245, v246, v247
	v_mad_i64_i32 v[14:15], s[20:21], v0, s4, v[2:3]
	global_store_dwordx2 v[14:15], v[244:245], off
	v_or_b32_e32 v0, 11, v10
	ds_read_b128 v[244:247], v6 offset:14560
	s_waitcnt lgkmcnt(3)
	v_cvt_pk_bf16_f32 v248, v248, v249
	v_cvt_pk_bf16_f32 v249, v250, v251
	v_mad_i64_i32 v[14:15], s[20:21], v0, s4, v[2:3]
	global_store_dwordx2 v[14:15], v[248:249], off
	v_or_b32_e32 v0, 12, v10
	s_waitcnt lgkmcnt(2)
	v_cvt_pk_bf16_f32 v236, v236, v237
	v_cvt_pk_bf16_f32 v237, v238, v239
	v_mad_i64_i32 v[14:15], s[20:21], v0, s4, v[2:3]
	global_store_dwordx2 v[14:15], v[236:237], off
	v_or_b32_e32 v0, 13, v10
	s_waitcnt lgkmcnt(1)
	v_cvt_pk_bf16_f32 v240, v240, v241
	v_cvt_pk_bf16_f32 v241, v242, v243
	v_mad_i64_i32 v[14:15], s[20:21], v0, s4, v[2:3]
	global_store_dwordx2 v[14:15], v[240:241], off
	v_or_b32_e32 v0, 14, v10
	s_waitcnt lgkmcnt(0)
	v_cvt_pk_bf16_f32 v6, v244, v245
	v_cvt_pk_bf16_f32 v7, v246, v247
	v_mad_i64_i32 v[10:11], s[20:21], v0, s4, v[2:3]
	v_or_b32_e32 v0, 15, v9
	global_store_dwordx2 v[10:11], v[6:7], off
	v_mad_u64_u32 v[6:7], s[20:21], v0, s36, v[4:5]
	v_mad_i64_i32 v[2:3], s[20:21], v0, s4, v[2:3]
	ds_read_b128 v[10:13], v6
	s_waitcnt lgkmcnt(0)
	v_cvt_pk_bf16_f32 v6, v10, v11
	v_cvt_pk_bf16_f32 v7, v12, v13
	global_store_dwordx2 v[2:3], v[6:7], off
	s_barrier
	s_and_saveexec_b64 s[20:21], vcc
	s_cbranch_execz .LBB0_573
	v_lshlrev_b32_e32 v0, 2, v5
	v_lshl_add_u32 v4, v8, 2, v0
	v_add_u32_e32 v2, 0x400, v4
	ds_write2_b32 v2, v129, v113 offset0:4 offset1:36
	v_add_u32_e32 v2, 0x800, v4
	ds_write2_b32 v2, v130, v114 offset0:8 offset1:40
	v_add_u32_e32 v2, 0xc00, v4
	ds_write2_b32 v2, v131, v115 offset0:12 offset1:44
	v_add_u32_e32 v2, 0x2000, v4
	ds_write2_b32 v2, v132, v116 offset0:32 offset1:64
	v_add_u32_e32 v2, 0x2400, v4
	ds_write2_b32 v2, v133, v117 offset0:36 offset1:68
	v_add_u32_e32 v2, 0x2800, v4
	ds_write2_b32 v2, v134, v118 offset0:40 offset1:72
	v_add_u32_e32 v2, 0x2c00, v4
	ds_write2_b32 v2, v135, v119 offset0:44 offset1:76
	v_add_u32_e32 v2, 0x4000, v4
	ds_write2_b32 v2, v136, v120 offset0:64 offset1:96
	v_add_u32_e32 v2, 0x4400, v4
	ds_write2_b32 v2, v137, v121 offset0:68 offset1:100
	v_add_u32_e32 v2, 0x4800, v4
	ds_write2_b32 v2, v138, v122 offset0:72 offset1:104
	v_add_u32_e32 v2, 0x4c00, v4
	ds_write2_b32 v2, v139, v123 offset0:76 offset1:108
	v_add_u32_e32 v2, 0x6000, v4
	ds_write2_b32 v2, v140, v124 offset0:96 offset1:128
	v_add_u32_e32 v2, 0x6400, v4
	ds_write2_b32 v2, v141, v125 offset0:100 offset1:132
	v_add_u32_e32 v2, 0x6800, v4
	ds_write2_b32 v2, v142, v126 offset0:104 offset1:136
	v_add_u32_e32 v2, 0x6c00, v4
	ds_write2_b32 v2, v143, v127 offset0:108 offset1:140
	v_add_u32_e32 v2, 0x8000, v4
	ds_write2_b32 v2, v96, v80 offset0:128 offset1:160
	v_add_u32_e32 v2, 0x8400, v4
	ds_write2_b32 v2, v97, v81 offset0:132 offset1:164
	v_add_u32_e32 v2, 0x8800, v4
	ds_write2_b32 v2, v98, v82 offset0:136 offset1:168
	v_add_u32_e32 v2, 0x8c00, v4
	ds_write2_b32 v2, v99, v83 offset0:140 offset1:172
	v_add_u32_e32 v2, 0xa000, v4
	ds_write2_b32 v2, v100, v84 offset0:160 offset1:192
	v_add_u32_e32 v2, 0xa400, v4
	ds_write2_b32 v2, v101, v85 offset0:164 offset1:196
	v_add_u32_e32 v2, 0xa800, v4
	ds_write2_b32 v2, v102, v86 offset0:168 offset1:200
	v_add_u32_e32 v2, 0xac00, v4
	ds_write2_b32 v2, v103, v87 offset0:172 offset1:204
	v_add_u32_e32 v2, 0xc000, v4
	ds_write2_b32 v2, v104, v88 offset0:192 offset1:224
	v_add_u32_e32 v2, 0xc400, v4
	ds_write2_b32 v2, v105, v89 offset0:196 offset1:228
	v_add_u32_e32 v2, 0xc800, v4
	ds_write2_b32 v2, v106, v90 offset0:200 offset1:232
	v_add_u32_e32 v2, 0xcc00, v4
	ds_write2_b32 v2, v107, v91 offset0:204 offset1:236
	v_add_u32_e32 v2, 0xe200, v4
	ds_write2_b32 v2, v108, v92 offset0:96 offset1:128
	v_add_u32_e32 v2, 0xe600, v4
	ds_write2_b32 v2, v109, v93 offset0:100 offset1:132
	v_add_u32_e32 v2, 0xea00, v4
	ds_write2_b32 v2, v110, v94 offset0:104 offset1:136
	v_add_u32_e32 v2, 0xee00, v4
	ds_write2_b32 v2, v111, v95 offset0:108 offset1:140
	v_add_u32_e32 v2, 0x10400, v4
	ds_write_b32 v2, v64
	v_add_u32_e32 v2, 0x10810, v4
	ds_write_b32 v2, v65
	v_add_u32_e32 v2, 0x10c20, v4
	ds_write_b32 v2, v66
	v_add_u32_e32 v2, 0x11030, v4
	ds_write_b32 v2, v67
	v_add_u32_e32 v2, 0x12480, v4
	ds_write_b32 v2, v68
	v_add_u32_e32 v2, 0x12890, v4
	ds_write_b32 v2, v69
	v_add_u32_e32 v2, 0x12ca0, v4
	ds_write_b32 v2, v70
	v_add_u32_e32 v2, 0x130b0, v4
	ds_write_b32 v2, v71
	v_add_u32_e32 v2, 0x14500, v4
	ds_write_b32 v2, v72
	v_add_u32_e32 v2, 0x14910, v4
	ds_write_b32 v2, v73
	v_add_u32_e32 v2, 0x14d20, v4
	ds_write_b32 v2, v74
	v_add_u32_e32 v2, 0x15130, v4
	ds_write_b32 v2, v75
	v_add_u32_e32 v2, 0x16580, v4
	ds_write_b32 v2, v76
	v_add_u32_e32 v2, 0x16990, v4
	ds_write_b32 v2, v77
	v_add_u32_e32 v2, 0x16da0, v4
	ds_write_b32 v2, v78
	v_add_u32_e32 v2, 0x171b0, v4
	ds_write_b32 v2, v79
	v_add_u32_e32 v2, 0x10480, v4
	ds_write_b32 v2, v48
	v_add_u32_e32 v2, 0x10890, v4
	ds_write_b32 v2, v49
	v_add_u32_e32 v2, 0x10ca0, v4
	ds_write_b32 v2, v50
	v_add_u32_e32 v2, 0x110b0, v4
	ds_write_b32 v2, v51
	v_add_u32_e32 v2, 0x12500, v4
	ds_write_b32 v2, v52
	v_add_u32_e32 v2, 0x12910, v4
	ds_write_b32 v2, v53
	v_add_u32_e32 v2, 0x12d20, v4
	ds_write_b32 v2, v54
	v_add_u32_e32 v2, 0x13130, v4
	ds_write_b32 v2, v55
	v_add_u32_e32 v2, 0x14580, v4
	ds_write_b32 v2, v56
	v_add_u32_e32 v2, 0x14990, v4
	ds_write_b32 v2, v57
	v_add_u32_e32 v2, 0x14da0, v4
	ds_write_b32 v2, v58
	v_add_u32_e32 v2, 0x151b0, v4
	ds_write_b32 v2, v59
	v_add_u32_e32 v2, 0x16600, v4
	ds_write_b32 v2, v60
	v_add_u32_e32 v2, 0x16a10, v4
	ds_write_b32 v2, v61
	v_add_u32_e32 v2, 0x16e20, v4
	ds_write_b32 v2, v62
	v_add_u32_e32 v2, 0x17230, v4
	ds_write_b32 v2, v63
	v_add_u32_e32 v2, 0x18600, v4
	ds_write_b32 v2, v32
	v_add_u32_e32 v2, 0x18a10, v4
	ds_write_b32 v2, v33
	v_add_u32_e32 v2, 0x18e20, v4
	ds_write_b32 v2, v34
	v_add_u32_e32 v2, 0x19230, v4
	ds_write_b32 v2, v35
	v_add_u32_e32 v2, 0x1a680, v4
	ds_write_b32 v2, v36
	v_add_u32_e32 v2, 0x1aa90, v4
	ds_write_b32 v2, v37
	v_add_u32_e32 v2, 0x1aea0, v4
	ds_write_b32 v2, v38
	v_add_u32_e32 v2, 0x1b2b0, v4
	ds_write_b32 v2, v39
	v_add_u32_e32 v2, 0x1c700, v4
	ds_write_b32 v2, v40
	v_add_u32_e32 v2, 0x1cb10, v4
	ds_write_b32 v2, v41
	v_add_u32_e32 v2, 0x1cf20, v4
	ds_write_b32 v2, v42
	v_add_u32_e32 v2, 0x1d330, v4
	ds_write_b32 v2, v43
	v_add_u32_e32 v2, 0x1e780, v4
	ds_write_b32 v2, v44
	v_add_u32_e32 v2, 0x1eb90, v4
	ds_write_b32 v2, v45
	v_add_u32_e32 v2, 0x1efa0, v4
	ds_write_b32 v2, v46
	v_mov_b32_e32 v2, 0x7b
	v_lshl_or_b32 v2, v192, 2, v2
	v_mad_u64_u32 v[2:3], s[28:29], v2, s36, v[0:1]
	v_add_u32_e32 v0, 0x18680, v4
	ds_write2_b32 v4, v128, v112 offset1:32
	ds_write_b32 v2, v47
	ds_write_b32 v0, v16
	v_add_u32_e32 v0, 0x18a90, v4
	ds_write_b32 v0, v17
	v_add_u32_e32 v0, 0x18ea0, v4
	ds_write_b32 v0, v18
	v_add_u32_e32 v0, 0x192b0, v4
	ds_write_b32 v0, v19
	v_add_u32_e32 v0, 0x1a700, v4
	ds_write_b32 v0, v20
	v_add_u32_e32 v0, 0x1ab10, v4
	ds_write_b32 v0, v21
	v_add_u32_e32 v0, 0x1af20, v4
	ds_write_b32 v0, v22
	v_add_u32_e32 v0, 0x1b330, v4
	ds_write_b32 v0, v23
	v_add_u32_e32 v0, 0x1c780, v4
	ds_write_b32 v0, v24
	v_add_u32_e32 v0, 0x1cb90, v4
	ds_write_b32 v0, v25
	v_add_u32_e32 v0, 0x1cfa0, v4
	ds_write_b32 v0, v26
	v_add_u32_e32 v0, 0x1d3b0, v4
	ds_write_b32 v0, v27
	v_add_u32_e32 v0, 0x1e800, v4
	ds_write_b32 v0, v28
	v_add_u32_e32 v0, 0x1ec10, v4
	ds_write_b32 v0, v29
	v_add_u32_e32 v0, 0x1f020, v4
	ds_write_b32 v0, v30
	ds_write_b32 v2, v31 offset:128
	s_branch .LBB0_573

.LBB0_619:
	s_or_b64 exec, exec, s[20:21]
	s_cmp_lt_i32 s48, 1
	s_mov_b64 s[20:21], -1
	s_waitcnt lgkmcnt(0)
	s_barrier
	s_cbranch_scc1 .LBB0_625
	s_cmp_lg_u32 s48, 1
	s_cbranch_scc0 .LBB0_622
	v_mov_b32_e32 v0, v206
	s_load_dwordx16 s[4:19], s[0:1], 0xa8
	v_lshlrev_b32_e32 v0, 4, v0
	v_and_b32_e32 v0, 0x3f0, v0
	v_or_b32_e32 v0, 0x21800, v0
	s_mul_i32 s21, s46, 0x9000
	ds_read_b128 v[2:5], v0
	v_mov_b32_e32 v0, v206
	s_mul_hi_i32 s20, s46, 0x9000
	s_waitcnt lgkmcnt(0)
	s_add_u32 s22, s14, s21
	s_addc_u32 s23, s15, s20
	s_lshl_b64 s[20:21], s[50:51], 1
	v_mov_b32_e32 v6, v206
	v_lshlrev_b32_e32 v0, 2, v0
	s_add_u32 s20, s22, s20
	v_and_b32_e32 v0, 0xfc, v0
	v_ashrrev_i32_e32 v9, 2, v6
	s_addc_u32 s21, s23, s21
	v_and_b32_e32 v12, -16, v9
	v_lshlrev_b32_e32 v8, 2, v0
	v_lshlrev_b32_e32 v0, 1, v0
	v_lshl_add_u64 v[6:7], s[20:21], 0, v[0:1]
	v_mad_u64_u32 v[10:11], s[20:21], v12, s36, v[8:9]
	ds_read_b128 v[236:239], v10
	ds_read_b128 v[240:243], v10 offset:1040
	ds_read_b128 v[244:247], v10 offset:2080
	ds_read_b128 v[248:251], v10 offset:3120
	s_mov_b32 s4, 0x9000
	v_or_b32_e32 v0, 1, v12
	s_waitcnt lgkmcnt(3)
	v_pk_mul_f32 v[14:15], v[4:5], v[238:239]
	v_pk_mul_f32 v[236:237], v[2:3], v[236:237]
	s_nop 0
	v_cvt_pk_bf16_f32 v236, v236, v237
	v_cvt_pk_bf16_f32 v237, v14, v15
	v_mad_i64_i32 v[14:15], s[20:21], v12, s4, v[6:7]
	global_store_dwordx2 v[14:15], v[236:237], off
	ds_read_b128 v[236:239], v10 offset:4160
	s_waitcnt lgkmcnt(3)
	v_pk_mul_f32 v[14:15], v[4:5], v[242:243]
	v_pk_mul_f32 v[240:241], v[2:3], v[240:241]
	s_nop 0
	v_cvt_pk_bf16_f32 v240, v240, v241
	v_cvt_pk_bf16_f32 v241, v14, v15
	v_mad_i64_i32 v[14:15], s[20:21], v0, s4, v[6:7]
	global_store_dwordx2 v[14:15], v[240:241], off
	ds_read_b128 v[240:243], v10 offset:5200
	v_or_b32_e32 v0, 2, v12
	s_waitcnt lgkmcnt(3)
	v_pk_mul_f32 v[14:15], v[4:5], v[246:247]
	v_pk_mul_f32 v[244:245], v[2:3], v[244:245]
	s_nop 0
	v_cvt_pk_bf16_f32 v244, v244, v245
	v_cvt_pk_bf16_f32 v245, v14, v15
	v_mad_i64_i32 v[14:15], s[20:21], v0, s4, v[6:7]
	global_store_dwordx2 v[14:15], v[244:245], off
	ds_read_b128 v[244:247], v10 offset:6240
	v_or_b32_e32 v0, 3, v12
	s_waitcnt lgkmcnt(3)
	v_pk_mul_f32 v[14:15], v[4:5], v[250:251]
	v_pk_mul_f32 v[248:249], v[2:3], v[248:249]
	s_nop 0
	v_cvt_pk_bf16_f32 v248, v248, v249
	v_cvt_pk_bf16_f32 v249, v14, v15
	v_mad_i64_i32 v[14:15], s[20:21], v0, s4, v[6:7]
	global_store_dwordx2 v[14:15], v[248:249], off
	ds_read_b128 v[248:251], v10 offset:7280
	v_or_b32_e32 v0, 4, v12
	s_waitcnt lgkmcnt(3)
	v_pk_mul_f32 v[14:15], v[4:5], v[238:239]
	v_pk_mul_f32 v[236:237], v[2:3], v[236:237]
	s_nop 0
	v_cvt_pk_bf16_f32 v236, v236, v237
	v_cvt_pk_bf16_f32 v237, v14, v15
	v_mad_i64_i32 v[14:15], s[20:21], v0, s4, v[6:7]
	global_store_dwordx2 v[14:15], v[236:237], off
	ds_read_b128 v[236:239], v10 offset:8320
	v_or_b32_e32 v0, 5, v12
	s_waitcnt lgkmcnt(3)
	v_pk_mul_f32 v[14:15], v[4:5], v[242:243]
	v_pk_mul_f32 v[240:241], v[2:3], v[240:241]
	s_nop 0
	v_cvt_pk_bf16_f32 v240, v240, v241
	v_cvt_pk_bf16_f32 v241, v14, v15
	v_mad_i64_i32 v[14:15], s[20:21], v0, s4, v[6:7]
	global_store_dwordx2 v[14:15], v[240:241], off
	ds_read_b128 v[240:243], v10 offset:9360
	v_or_b32_e32 v0, 6, v12
	s_waitcnt lgkmcnt(3)
	v_pk_mul_f32 v[14:15], v[4:5], v[246:247]
	v_pk_mul_f32 v[244:245], v[2:3], v[244:245]
	s_nop 0
	v_cvt_pk_bf16_f32 v244, v244, v245
	v_cvt_pk_bf16_f32 v245, v14, v15
	v_mad_i64_i32 v[14:15], s[20:21], v0, s4, v[6:7]
	global_store_dwordx2 v[14:15], v[244:245], off
	ds_read_b128 v[244:247], v10 offset:10400
	v_or_b32_e32 v0, 7, v12
	s_waitcnt lgkmcnt(3)
	v_pk_mul_f32 v[14:15], v[4:5], v[250:251]
	v_pk_mul_f32 v[248:249], v[2:3], v[248:249]
	s_nop 0
	v_cvt_pk_bf16_f32 v248, v248, v249
	v_cvt_pk_bf16_f32 v249, v14, v15
	v_mad_i64_i32 v[14:15], s[20:21], v0, s4, v[6:7]
	global_store_dwordx2 v[14:15], v[248:249], off
	ds_read_b128 v[248:251], v10 offset:11440
	v_or_b32_e32 v0, 8, v12
	s_waitcnt lgkmcnt(3)
	v_pk_mul_f32 v[14:15], v[4:5], v[238:239]
	v_pk_mul_f32 v[236:237], v[2:3], v[236:237]
	s_nop 0
	v_cvt_pk_bf16_f32 v236, v236, v237
	v_cvt_pk_bf16_f32 v237, v14, v15
	v_mad_i64_i32 v[14:15], s[20:21], v0, s4, v[6:7]
	global_store_dwordx2 v[14:15], v[236:237], off
	ds_read_b128 v[236:239], v10 offset:12480
	v_or_b32_e32 v0, 9, v12
	s_waitcnt lgkmcnt(3)
	v_pk_mul_f32 v[14:15], v[4:5], v[242:243]
	v_pk_mul_f32 v[240:241], v[2:3], v[240:241]
	s_nop 0
	v_cvt_pk_bf16_f32 v240, v240, v241
	v_cvt_pk_bf16_f32 v241, v14, v15
	v_mad_i64_i32 v[14:15], s[20:21], v0, s4, v[6:7]
	global_store_dwordx2 v[14:15], v[240:241], off
	ds_read_b128 v[240:243], v10 offset:13520
	v_or_b32_e32 v0, 10, v12
	s_waitcnt lgkmcnt(3)
	v_pk_mul_f32 v[14:15], v[4:5], v[246:247]
	v_pk_mul_f32 v[244:245], v[2:3], v[244:245]
	s_nop 0
	v_cvt_pk_bf16_f32 v244, v244, v245
	v_cvt_pk_bf16_f32 v245, v14, v15
	v_mad_i64_i32 v[14:15], s[20:21], v0, s4, v[6:7]
	global_store_dwordx2 v[14:15], v[244:245], off
	ds_read_b128 v[244:247], v10 offset:14560
	v_or_b32_e32 v0, 11, v12
	s_waitcnt lgkmcnt(3)
	v_pk_mul_f32 v[14:15], v[4:5], v[250:251]
	v_pk_mul_f32 v[248:249], v[2:3], v[248:249]
	s_nop 0
	v_cvt_pk_bf16_f32 v248, v248, v249
	v_cvt_pk_bf16_f32 v249, v14, v15
	v_mad_i64_i32 v[14:15], s[20:21], v0, s4, v[6:7]
	global_store_dwordx2 v[14:15], v[248:249], off
	v_or_b32_e32 v0, 12, v12
	s_waitcnt lgkmcnt(2)
	v_pk_mul_f32 v[14:15], v[4:5], v[238:239]
	v_pk_mul_f32 v[236:237], v[2:3], v[236:237]
	s_nop 0
	v_cvt_pk_bf16_f32 v236, v236, v237
	v_cvt_pk_bf16_f32 v237, v14, v15
	v_mad_i64_i32 v[14:15], s[20:21], v0, s4, v[6:7]
	global_store_dwordx2 v[14:15], v[236:237], off
	v_or_b32_e32 v0, 13, v12
	s_waitcnt lgkmcnt(1)
	v_pk_mul_f32 v[14:15], v[4:5], v[242:243]
	v_pk_mul_f32 v[144:145], v[2:3], v[240:241]
	s_nop 0
	v_cvt_pk_bf16_f32 v144, v144, v145
	v_cvt_pk_bf16_f32 v145, v14, v15
	v_mad_i64_i32 v[14:15], s[20:21], v0, s4, v[6:7]
	v_or_b32_e32 v0, 14, v12
	global_store_dwordx2 v[14:15], v[144:145], off
	s_waitcnt lgkmcnt(0)
	v_pk_mul_f32 v[246:247], v[4:5], v[246:247]
	v_pk_mul_f32 v[244:245], v[2:3], v[244:245]
	s_nop 0
	v_cvt_pk_bf16_f32 v244, v244, v245
	v_cvt_pk_bf16_f32 v245, v246, v247
	v_mad_i64_i32 v[12:13], s[20:21], v0, s4, v[6:7]
	v_or_b32_e32 v0, 15, v9
	v_mad_u64_u32 v[8:9], s[20:21], v0, s36, v[8:9]
	global_store_dwordx2 v[12:13], v[244:245], off
	ds_read_b128 v[8:11], v8
	s_waitcnt lgkmcnt(0)
	v_pk_mul_f32 v[4:5], v[4:5], v[10:11]
	v_pk_mul_f32 v[2:3], v[2:3], v[8:9]
	s_nop 0
	v_cvt_pk_bf16_f32 v2, v2, v3
	v_cvt_pk_bf16_f32 v3, v4, v5
	v_mad_i64_i32 v[4:5], s[20:21], v0, s4, v[6:7]
	global_store_dwordx2 v[4:5], v[2:3], off
	s_mov_b64 s[20:21], 0

.LBB0_633:
	s_or_b64 exec, exec, s[20:21]
	s_cmp_lt_i32 s48, 1
	s_mov_b64 s[20:21], -1
	s_waitcnt lgkmcnt(0)
	s_barrier
	s_cbranch_scc1 .LBB0_639
	s_cmp_lg_u32 s48, 1
	s_cbranch_scc0 .LBB0_636
	v_mov_b32_e32 v0, v206
	s_load_dwordx16 s[4:19], s[0:1], 0xa8
	v_lshlrev_b32_e32 v0, 4, v0
	v_and_b32_e32 v0, 0x3f0, v0
	v_or_b32_e32 v0, 0x21800, v0
	s_mul_i32 s21, s46, 0x9000
	ds_read_b128 v[2:5], v0
	v_mov_b32_e32 v0, v206
	s_mul_hi_i32 s20, s46, 0x9000
	s_waitcnt lgkmcnt(0)
	s_add_u32 s26, s14, s21
	s_addc_u32 s27, s15, s20
	s_lshl_b64 s[20:21], s[50:51], 1
	v_mov_b32_e32 v6, v206
	v_lshlrev_b32_e32 v0, 2, v0
	s_add_u32 s20, s26, s20
	v_and_b32_e32 v0, 0xfc, v0
	v_ashrrev_i32_e32 v9, 2, v6
	s_addc_u32 s21, s27, s21
	v_and_b32_e32 v12, -16, v9
	v_lshlrev_b32_e32 v8, 2, v0
	v_lshlrev_b32_e32 v0, 1, v0
	v_lshl_add_u64 v[6:7], s[20:21], 0, v[0:1]
	v_mad_u64_u32 v[10:11], s[20:21], v12, s36, v[8:9]
	ds_read_b128 v[236:239], v10
	ds_read_b128 v[240:243], v10 offset:1040
	ds_read_b128 v[244:247], v10 offset:2080
	ds_read_b128 v[248:251], v10 offset:3120
	v_add_u32_e32 v0, 0x80, v12
	s_mov_b32 s4, 0x9000
	s_waitcnt lgkmcnt(3)
	v_pk_mul_f32 v[238:239], v[4:5], v[238:239]
	v_pk_mul_f32 v[236:237], v[2:3], v[236:237]
	s_nop 0
	v_cvt_pk_bf16_f32 v236, v236, v237
	v_cvt_pk_bf16_f32 v237, v238, v239
	v_mad_i64_i32 v[16:17], s[20:21], v0, s4, v[6:7]
	global_store_dwordx2 v[16:17], v[236:237], off
	ds_read_b128 v[236:239], v10 offset:4160
	v_add_u32_e32 v0, 0x81, v12
	s_waitcnt lgkmcnt(3)
	v_pk_mul_f32 v[242:243], v[4:5], v[242:243]
	v_pk_mul_f32 v[240:241], v[2:3], v[240:241]
	s_nop 0
	v_cvt_pk_bf16_f32 v240, v240, v241
	v_cvt_pk_bf16_f32 v241, v242, v243
	v_mad_i64_i32 v[16:17], s[20:21], v0, s4, v[6:7]
	global_store_dwordx2 v[16:17], v[240:241], off
	ds_read_b128 v[240:243], v10 offset:5200
	v_add_u32_e32 v0, 0x82, v12
	s_waitcnt lgkmcnt(3)
	v_pk_mul_f32 v[246:247], v[4:5], v[246:247]
	v_pk_mul_f32 v[244:245], v[2:3], v[244:245]
	s_nop 0
	v_cvt_pk_bf16_f32 v244, v244, v245
	v_cvt_pk_bf16_f32 v245, v246, v247
	v_mad_i64_i32 v[16:17], s[20:21], v0, s4, v[6:7]
	global_store_dwordx2 v[16:17], v[244:245], off
	ds_read_b128 v[244:247], v10 offset:6240
	v_add_u32_e32 v0, 0x83, v12
	s_waitcnt lgkmcnt(3)
	v_pk_mul_f32 v[250:251], v[4:5], v[250:251]
	v_pk_mul_f32 v[248:249], v[2:3], v[248:249]
	s_nop 0
	v_cvt_pk_bf16_f32 v248, v248, v249
	v_cvt_pk_bf16_f32 v249, v250, v251
	v_mad_i64_i32 v[16:17], s[20:21], v0, s4, v[6:7]
	global_store_dwordx2 v[16:17], v[248:249], off
	ds_read_b128 v[248:251], v10 offset:7280
	v_add_u32_e32 v0, 0x84, v12
	s_waitcnt lgkmcnt(3)
	v_pk_mul_f32 v[238:239], v[4:5], v[238:239]
	v_pk_mul_f32 v[236:237], v[2:3], v[236:237]
	s_nop 0
	v_cvt_pk_bf16_f32 v236, v236, v237
	v_cvt_pk_bf16_f32 v237, v238, v239
	v_mad_i64_i32 v[16:17], s[20:21], v0, s4, v[6:7]
	global_store_dwordx2 v[16:17], v[236:237], off
	ds_read_b128 v[236:239], v10 offset:8320
	v_add_u32_e32 v0, 0x85, v12
	s_waitcnt lgkmcnt(3)
	v_pk_mul_f32 v[242:243], v[4:5], v[242:243]
	v_pk_mul_f32 v[240:241], v[2:3], v[240:241]
	s_nop 0
	v_cvt_pk_bf16_f32 v240, v240, v241
	v_cvt_pk_bf16_f32 v241, v242, v243
	v_mad_i64_i32 v[16:17], s[20:21], v0, s4, v[6:7]
	global_store_dwordx2 v[16:17], v[240:241], off
	ds_read_b128 v[240:243], v10 offset:9360
	v_add_u32_e32 v0, 0x86, v12
	s_waitcnt lgkmcnt(3)
	v_pk_mul_f32 v[246:247], v[4:5], v[246:247]
	v_pk_mul_f32 v[244:245], v[2:3], v[244:245]
	s_nop 0
	v_cvt_pk_bf16_f32 v244, v244, v245
	v_cvt_pk_bf16_f32 v245, v246, v247
	v_mad_i64_i32 v[16:17], s[20:21], v0, s4, v[6:7]
	global_store_dwordx2 v[16:17], v[244:245], off
	ds_read_b128 v[244:247], v10 offset:10400
	v_add_u32_e32 v0, 0x87, v12
	s_waitcnt lgkmcnt(3)
	v_pk_mul_f32 v[250:251], v[4:5], v[250:251]
	v_pk_mul_f32 v[248:249], v[2:3], v[248:249]
	s_nop 0
	v_cvt_pk_bf16_f32 v248, v248, v249
	v_cvt_pk_bf16_f32 v249, v250, v251
	v_mad_i64_i32 v[16:17], s[20:21], v0, s4, v[6:7]
	global_store_dwordx2 v[16:17], v[248:249], off
	ds_read_b128 v[248:251], v10 offset:11440
	v_add_u32_e32 v0, 0x88, v12
	s_waitcnt lgkmcnt(3)
	v_pk_mul_f32 v[238:239], v[4:5], v[238:239]
	v_pk_mul_f32 v[236:237], v[2:3], v[236:237]
	s_nop 0
	v_cvt_pk_bf16_f32 v236, v236, v237
	v_cvt_pk_bf16_f32 v237, v238, v239
	v_mad_i64_i32 v[16:17], s[20:21], v0, s4, v[6:7]
	global_store_dwordx2 v[16:17], v[236:237], off
	ds_read_b128 v[236:239], v10 offset:12480
	v_add_u32_e32 v0, 0x89, v12
	s_waitcnt lgkmcnt(3)
	v_pk_mul_f32 v[242:243], v[4:5], v[242:243]
	v_pk_mul_f32 v[240:241], v[2:3], v[240:241]
	s_nop 0
	v_cvt_pk_bf16_f32 v240, v240, v241
	v_cvt_pk_bf16_f32 v241, v242, v243
	v_mad_i64_i32 v[16:17], s[20:21], v0, s4, v[6:7]
	global_store_dwordx2 v[16:17], v[240:241], off
	ds_read_b128 v[240:243], v10 offset:13520
	v_add_u32_e32 v0, 0x8a, v12
	s_waitcnt lgkmcnt(3)
	v_pk_mul_f32 v[246:247], v[4:5], v[246:247]
	v_pk_mul_f32 v[244:245], v[2:3], v[244:245]
	s_nop 0
	v_cvt_pk_bf16_f32 v244, v244, v245
	v_cvt_pk_bf16_f32 v245, v246, v247
	v_mad_i64_i32 v[16:17], s[20:21], v0, s4, v[6:7]
	global_store_dwordx2 v[16:17], v[244:245], off
	ds_read_b128 v[244:247], v10 offset:14560
	v_add_u32_e32 v0, 0x8b, v12
	s_waitcnt lgkmcnt(3)
	v_pk_mul_f32 v[250:251], v[4:5], v[250:251]
	v_pk_mul_f32 v[248:249], v[2:3], v[248:249]
	s_nop 0
	v_cvt_pk_bf16_f32 v248, v248, v249
	v_cvt_pk_bf16_f32 v249, v250, v251
	v_mad_i64_i32 v[16:17], s[20:21], v0, s4, v[6:7]
	global_store_dwordx2 v[16:17], v[248:249], off
	v_add_u32_e32 v0, 0x8c, v12
	s_waitcnt lgkmcnt(2)
	v_pk_mul_f32 v[238:239], v[4:5], v[238:239]
	v_pk_mul_f32 v[236:237], v[2:3], v[236:237]
	s_nop 0
	v_cvt_pk_bf16_f32 v236, v236, v237
	v_cvt_pk_bf16_f32 v237, v238, v239
	v_mad_i64_i32 v[16:17], s[20:21], v0, s4, v[6:7]
	global_store_dwordx2 v[16:17], v[236:237], off
	v_add_u32_e32 v0, 0x8d, v12
	s_waitcnt lgkmcnt(1)
	v_pk_mul_f32 v[16:17], v[4:5], v[242:243]
	v_pk_mul_f32 v[14:15], v[2:3], v[240:241]
	s_nop 0
	v_cvt_pk_bf16_f32 v14, v14, v15
	v_cvt_pk_bf16_f32 v15, v16, v17
	v_mad_i64_i32 v[16:17], s[20:21], v0, s4, v[6:7]
	v_add_u32_e32 v0, 0x8e, v12
	global_store_dwordx2 v[16:17], v[14:15], off
	s_waitcnt lgkmcnt(0)
	v_pk_mul_f32 v[246:247], v[4:5], v[246:247]
	v_pk_mul_f32 v[244:245], v[2:3], v[244:245]
	s_nop 0
	v_cvt_pk_bf16_f32 v244, v244, v245
	v_cvt_pk_bf16_f32 v245, v246, v247
	v_mad_i64_i32 v[12:13], s[20:21], v0, s4, v[6:7]
	v_or_b32_e32 v0, 15, v9
	v_mad_u64_u32 v[8:9], s[20:21], v0, s36, v[8:9]
	global_store_dwordx2 v[12:13], v[244:245], off
	ds_read_b128 v[8:11], v8
	v_add_u32_e32 v12, 0x80, v0
	s_waitcnt lgkmcnt(0)
	v_pk_mul_f32 v[4:5], v[4:5], v[10:11]
	v_pk_mul_f32 v[2:3], v[2:3], v[8:9]
	s_nop 0
	v_cvt_pk_bf16_f32 v2, v2, v3
	v_cvt_pk_bf16_f32 v3, v4, v5
	v_mad_i64_i32 v[4:5], s[20:21], v12, s4, v[6:7]
	global_store_dwordx2 v[4:5], v[2:3], off
	s_mov_b64 s[20:21], 0

.LBB0_731:
	s_or_b64 exec, exec, s[20:21]
	s_mov_b64 s[20:21], -1
	s_andn2_b64 vcc, exec, s[58:59]
	s_mul_hi_i32 s22, s56, 0x9000
	s_mul_i32 s23, s56, 0x9000
	s_waitcnt lgkmcnt(0)
	s_barrier
	s_cbranch_vccnz .LBB0_733
	s_load_dwordx16 s[4:19], s[0:1], 0xa8
	v_mov_b32_e32 v0, v206
	v_mov_b32_e32 v2, v206
	v_lshlrev_b32_e32 v0, 2, v0
	s_waitcnt lgkmcnt(0)
	s_add_u32 s26, s14, s23
	s_addc_u32 s27, s15, s22
	s_lshl_b64 s[20:21], s[54:55], 1
	s_add_u32 s20, s26, s20
	v_and_b32_e32 v0, 0xfc, v0
	v_ashrrev_i32_e32 v5, 2, v2
	s_addc_u32 s21, s27, s21
	v_and_b32_e32 v8, -16, v5
	v_lshlrev_b32_e32 v4, 2, v0
	v_lshlrev_b32_e32 v0, 1, v0
	v_lshl_add_u64 v[2:3], s[20:21], 0, v[0:1]
	v_mad_u64_u32 v[6:7], s[20:21], v8, s36, v[4:5]
	ds_read_b128 v[236:239], v6
	ds_read_b128 v[240:243], v6 offset:1040
	ds_read_b128 v[244:247], v6 offset:2080
	ds_read_b128 v[248:251], v6 offset:3120
	s_mov_b32 s4, 0x9000
	s_waitcnt lgkmcnt(3)
	v_cvt_pk_bf16_f32 v236, v236, v237
	v_cvt_pk_bf16_f32 v237, v238, v239
	v_mad_i64_i32 v[12:13], s[20:21], v8, s4, v[2:3]
	global_store_dwordx2 v[12:13], v[236:237], off
	v_or_b32_e32 v0, 1, v8
	ds_read_b128 v[236:239], v6 offset:4160
	s_waitcnt lgkmcnt(3)
	v_cvt_pk_bf16_f32 v240, v240, v241
	v_cvt_pk_bf16_f32 v241, v242, v243
	v_mad_i64_i32 v[12:13], s[20:21], v0, s4, v[2:3]
	global_store_dwordx2 v[12:13], v[240:241], off
	v_or_b32_e32 v0, 2, v8
	ds_read_b128 v[240:243], v6 offset:5200
	s_waitcnt lgkmcnt(3)
	v_cvt_pk_bf16_f32 v244, v244, v245
	v_cvt_pk_bf16_f32 v245, v246, v247
	v_mad_i64_i32 v[12:13], s[20:21], v0, s4, v[2:3]
	global_store_dwordx2 v[12:13], v[244:245], off
	v_or_b32_e32 v0, 3, v8
	ds_read_b128 v[244:247], v6 offset:6240
	s_waitcnt lgkmcnt(3)
	v_cvt_pk_bf16_f32 v248, v248, v249
	v_cvt_pk_bf16_f32 v249, v250, v251
	v_mad_i64_i32 v[12:13], s[20:21], v0, s4, v[2:3]
	global_store_dwordx2 v[12:13], v[248:249], off
	v_or_b32_e32 v0, 4, v8
	ds_read_b128 v[248:251], v6 offset:7280
	s_waitcnt lgkmcnt(3)
	v_cvt_pk_bf16_f32 v236, v236, v237
	v_cvt_pk_bf16_f32 v237, v238, v239
	v_mad_i64_i32 v[12:13], s[20:21], v0, s4, v[2:3]
	global_store_dwordx2 v[12:13], v[236:237], off
	v_or_b32_e32 v0, 5, v8
	ds_read_b128 v[236:239], v6 offset:8320
	s_waitcnt lgkmcnt(3)
	v_cvt_pk_bf16_f32 v240, v240, v241
	v_cvt_pk_bf16_f32 v241, v242, v243
	v_mad_i64_i32 v[12:13], s[20:21], v0, s4, v[2:3]
	global_store_dwordx2 v[12:13], v[240:241], off
	v_or_b32_e32 v0, 6, v8
	ds_read_b128 v[240:243], v6 offset:9360
	s_waitcnt lgkmcnt(3)
	v_cvt_pk_bf16_f32 v244, v244, v245
	v_cvt_pk_bf16_f32 v245, v246, v247
	v_mad_i64_i32 v[12:13], s[20:21], v0, s4, v[2:3]
	global_store_dwordx2 v[12:13], v[244:245], off
	v_or_b32_e32 v0, 7, v8
	ds_read_b128 v[244:247], v6 offset:10400
	s_waitcnt lgkmcnt(3)
	v_cvt_pk_bf16_f32 v248, v248, v249
	v_cvt_pk_bf16_f32 v249, v250, v251
	v_mad_i64_i32 v[12:13], s[20:21], v0, s4, v[2:3]
	global_store_dwordx2 v[12:13], v[248:249], off
	v_or_b32_e32 v0, 8, v8
	ds_read_b128 v[248:251], v6 offset:11440
	s_waitcnt lgkmcnt(3)
	v_cvt_pk_bf16_f32 v236, v236, v237
	v_cvt_pk_bf16_f32 v237, v238, v239
	v_mad_i64_i32 v[12:13], s[20:21], v0, s4, v[2:3]
	global_store_dwordx2 v[12:13], v[236:237], off
	v_or_b32_e32 v0, 9, v8
	ds_read_b128 v[236:239], v6 offset:12480
	s_waitcnt lgkmcnt(3)
	v_cvt_pk_bf16_f32 v240, v240, v241
	v_cvt_pk_bf16_f32 v241, v242, v243
	v_mad_i64_i32 v[12:13], s[20:21], v0, s4, v[2:3]
	global_store_dwordx2 v[12:13], v[240:241], off
	v_or_b32_e32 v0, 10, v8
	ds_read_b128 v[240:243], v6 offset:13520
	s_waitcnt lgkmcnt(3)
	v_cvt_pk_bf16_f32 v244, v244, v245
	v_cvt_pk_bf16_f32 v245, v246, v247
	v_mad_i64_i32 v[12:13], s[20:21], v0, s4, v[2:3]
	global_store_dwordx2 v[12:13], v[244:245], off
	v_or_b32_e32 v0, 11, v8
	ds_read_b128 v[244:247], v6 offset:14560
	s_waitcnt lgkmcnt(3)
	v_cvt_pk_bf16_f32 v248, v248, v249
	v_cvt_pk_bf16_f32 v249, v250, v251
	v_mad_i64_i32 v[12:13], s[20:21], v0, s4, v[2:3]
	global_store_dwordx2 v[12:13], v[248:249], off
	v_or_b32_e32 v0, 12, v8
	s_waitcnt lgkmcnt(2)
	v_cvt_pk_bf16_f32 v236, v236, v237
	v_cvt_pk_bf16_f32 v237, v238, v239
	v_mad_i64_i32 v[12:13], s[20:21], v0, s4, v[2:3]
	global_store_dwordx2 v[12:13], v[236:237], off
	v_or_b32_e32 v0, 13, v8
	s_waitcnt lgkmcnt(1)
	v_cvt_pk_bf16_f32 v10, v240, v241
	v_cvt_pk_bf16_f32 v11, v242, v243
	v_mad_i64_i32 v[12:13], s[20:21], v0, s4, v[2:3]
	v_or_b32_e32 v0, 14, v8
	s_waitcnt lgkmcnt(0)
	v_cvt_pk_bf16_f32 v244, v244, v245
	v_cvt_pk_bf16_f32 v245, v246, v247
	v_mad_i64_i32 v[8:9], s[20:21], v0, s4, v[2:3]
	v_or_b32_e32 v0, 15, v5
	v_mad_u64_u32 v[4:5], s[20:21], v0, s36, v[4:5]
	v_mad_i64_i32 v[2:3], s[20:21], v0, s4, v[2:3]
	global_store_dwordx2 v[8:9], v[244:245], off
	ds_read_b128 v[4:7], v4
	s_mov_b64 s[20:21], 0
	global_store_dwordx2 v[12:13], v[10:11], off
	s_waitcnt lgkmcnt(0)
	v_cvt_pk_bf16_f32 v4, v4, v5
	v_cvt_pk_bf16_f32 v5, v6, v7
	global_store_dwordx2 v[2:3], v[4:5], off

.LBB0_748:
	s_or_b64 exec, exec, s[20:21]
	s_mov_b64 s[20:21], -1
	s_and_b64 vcc, exec, s[58:59]
	s_waitcnt lgkmcnt(0)
	s_barrier
	s_cbranch_vccz .LBB0_750
	s_load_dwordx16 s[4:19], s[0:1], 0xa8
	v_mov_b32_e32 v0, v206
	v_mov_b32_e32 v2, v206
	v_lshlrev_b32_e32 v0, 2, v0
	s_waitcnt lgkmcnt(0)
	s_add_u32 s23, s14, s23
	s_addc_u32 s22, s15, s22
	s_lshl_b64 s[20:21], s[54:55], 1
	s_add_u32 s20, s23, s20
	v_and_b32_e32 v0, 0xfc, v0
	v_ashrrev_i32_e32 v5, 2, v2
	s_addc_u32 s21, s22, s21
	v_and_b32_e32 v8, -16, v5
	v_lshlrev_b32_e32 v4, 2, v0
	v_lshlrev_b32_e32 v0, 1, v0
	v_lshl_add_u64 v[2:3], s[20:21], 0, v[0:1]
	v_mad_u64_u32 v[6:7], s[20:21], v8, s36, v[4:5]
	v_add_u32_e32 v0, 0x80, v8
	ds_read_b128 v[236:239], v6
	ds_read_b128 v[240:243], v6 offset:1040
	ds_read_b128 v[244:247], v6 offset:2080
	ds_read_b128 v[248:251], v6 offset:3120
	s_mov_b32 s4, 0x9000
	s_waitcnt lgkmcnt(3)
	v_cvt_pk_bf16_f32 v236, v236, v237
	v_cvt_pk_bf16_f32 v237, v238, v239
	v_mad_i64_i32 v[12:13], s[20:21], v0, s4, v[2:3]
	global_store_dwordx2 v[12:13], v[236:237], off
	v_add_u32_e32 v0, 0x81, v8
	ds_read_b128 v[236:239], v6 offset:4160
	s_waitcnt lgkmcnt(3)
	v_cvt_pk_bf16_f32 v240, v240, v241
	v_cvt_pk_bf16_f32 v241, v242, v243
	v_mad_i64_i32 v[12:13], s[20:21], v0, s4, v[2:3]
	global_store_dwordx2 v[12:13], v[240:241], off
	v_add_u32_e32 v0, 0x82, v8
	ds_read_b128 v[240:243], v6 offset:5200
	s_waitcnt lgkmcnt(3)
	v_cvt_pk_bf16_f32 v244, v244, v245
	v_cvt_pk_bf16_f32 v245, v246, v247
	v_mad_i64_i32 v[12:13], s[20:21], v0, s4, v[2:3]
	global_store_dwordx2 v[12:13], v[244:245], off
	v_add_u32_e32 v0, 0x83, v8
	ds_read_b128 v[244:247], v6 offset:6240
	s_waitcnt lgkmcnt(3)
	v_cvt_pk_bf16_f32 v248, v248, v249
	v_cvt_pk_bf16_f32 v249, v250, v251
	v_mad_i64_i32 v[12:13], s[20:21], v0, s4, v[2:3]
	global_store_dwordx2 v[12:13], v[248:249], off
	v_add_u32_e32 v0, 0x84, v8
	ds_read_b128 v[248:251], v6 offset:7280
	s_waitcnt lgkmcnt(3)
	v_cvt_pk_bf16_f32 v236, v236, v237
	v_cvt_pk_bf16_f32 v237, v238, v239
	v_mad_i64_i32 v[12:13], s[20:21], v0, s4, v[2:3]
	global_store_dwordx2 v[12:13], v[236:237], off
	v_add_u32_e32 v0, 0x85, v8
	ds_read_b128 v[236:239], v6 offset:8320
	s_waitcnt lgkmcnt(3)
	v_cvt_pk_bf16_f32 v240, v240, v241
	v_cvt_pk_bf16_f32 v241, v242, v243
	v_mad_i64_i32 v[12:13], s[20:21], v0, s4, v[2:3]
	global_store_dwordx2 v[12:13], v[240:241], off
	v_add_u32_e32 v0, 0x86, v8
	ds_read_b128 v[240:243], v6 offset:9360
	s_waitcnt lgkmcnt(3)
	v_cvt_pk_bf16_f32 v244, v244, v245
	v_cvt_pk_bf16_f32 v245, v246, v247
	v_mad_i64_i32 v[12:13], s[20:21], v0, s4, v[2:3]
	global_store_dwordx2 v[12:13], v[244:245], off
	v_add_u32_e32 v0, 0x87, v8
	ds_read_b128 v[244:247], v6 offset:10400
	s_waitcnt lgkmcnt(3)
	v_cvt_pk_bf16_f32 v248, v248, v249
	v_cvt_pk_bf16_f32 v249, v250, v251
	v_mad_i64_i32 v[12:13], s[20:21], v0, s4, v[2:3]
	global_store_dwordx2 v[12:13], v[248:249], off
	v_add_u32_e32 v0, 0x88, v8
	ds_read_b128 v[248:251], v6 offset:11440
	s_waitcnt lgkmcnt(3)
	v_cvt_pk_bf16_f32 v236, v236, v237
	v_cvt_pk_bf16_f32 v237, v238, v239
	v_mad_i64_i32 v[12:13], s[20:21], v0, s4, v[2:3]
	global_store_dwordx2 v[12:13], v[236:237], off
	v_add_u32_e32 v0, 0x89, v8
	ds_read_b128 v[236:239], v6 offset:12480
	s_waitcnt lgkmcnt(3)
	v_cvt_pk_bf16_f32 v240, v240, v241
	v_cvt_pk_bf16_f32 v241, v242, v243
	v_mad_i64_i32 v[12:13], s[20:21], v0, s4, v[2:3]
	global_store_dwordx2 v[12:13], v[240:241], off
	v_add_u32_e32 v0, 0x8a, v8
	ds_read_b128 v[240:243], v6 offset:13520
	s_waitcnt lgkmcnt(3)
	v_cvt_pk_bf16_f32 v244, v244, v245
	v_cvt_pk_bf16_f32 v245, v246, v247
	v_mad_i64_i32 v[12:13], s[20:21], v0, s4, v[2:3]
	global_store_dwordx2 v[12:13], v[244:245], off
	v_add_u32_e32 v0, 0x8b, v8
	ds_read_b128 v[244:247], v6 offset:14560
	s_waitcnt lgkmcnt(3)
	v_cvt_pk_bf16_f32 v248, v248, v249
	v_cvt_pk_bf16_f32 v249, v250, v251
	v_mad_i64_i32 v[12:13], s[20:21], v0, s4, v[2:3]
	global_store_dwordx2 v[12:13], v[248:249], off
	v_add_u32_e32 v0, 0x8c, v8
	s_waitcnt lgkmcnt(2)
	v_cvt_pk_bf16_f32 v236, v236, v237
	v_cvt_pk_bf16_f32 v237, v238, v239
	v_mad_i64_i32 v[12:13], s[20:21], v0, s4, v[2:3]
	global_store_dwordx2 v[12:13], v[236:237], off
	v_add_u32_e32 v0, 0x8d, v8
	s_waitcnt lgkmcnt(1)
	v_cvt_pk_bf16_f32 v10, v240, v241
	v_cvt_pk_bf16_f32 v11, v242, v243
	v_mad_i64_i32 v[12:13], s[20:21], v0, s4, v[2:3]
	v_add_u32_e32 v0, 0x8e, v8
	s_waitcnt lgkmcnt(0)
	v_cvt_pk_bf16_f32 v244, v244, v245
	v_cvt_pk_bf16_f32 v245, v246, v247
	v_mad_i64_i32 v[8:9], s[20:21], v0, s4, v[2:3]
	v_or_b32_e32 v0, 15, v5
	global_store_dwordx2 v[8:9], v[244:245], off
	v_add_u32_e32 v8, 0x80, v0
	v_mad_u64_u32 v[4:5], s[20:21], v0, s36, v[4:5]
	ds_read_b128 v[4:7], v4
	v_mad_i64_i32 v[2:3], s[20:21], v8, s4, v[2:3]
	global_store_dwordx2 v[12:13], v[10:11], off
	s_waitcnt lgkmcnt(0)
	v_cvt_pk_bf16_f32 v4, v4, v5
	v_cvt_pk_bf16_f32 v5, v6, v7
	global_store_dwordx2 v[2:3], v[4:5], off
	s_mov_b64 s[20:21], 0
